# MLA attention loop: waves 4-7 staggered half a step behind waves 0-3 (QK part / softmax+PV part split by a second barrier), K/V tile staging moved to the end of the QK part
# speedup vs baseline: 2.5715x; 2.5715x over previous
; #define LAS __attribute__((address_space(3)))
; __device__ __forceinline__ bf16_t bf1(float x) { return (bf16_t)(cvtpk(x, x) & 0xffffu); }
; #define MFMA32(a, b, c) __builtin_amdgcn_mfma_f32_32x32x16_bf16((a), (b), (c), 0, 0, 0)
; __device__ __forceinline__ void mla_block(int bh, int sb, int tid, int lane, int wave, LAS unsigned char* lds, const bf16_t* __restrict__ QM, const bf16_t* __restrict__ KVM, const bf16_t* __restrict__ KPE, ...
;     ...
;     rk = *(const v4u*)gKn; rr = *(const v4u*)gKr; rv = *(const v4u*)gVt;
; #pragma unroll
;     for (int j = 0; j < 8; ++j) { const float cs = j < 4 ? rc0_[j & 3] : rc1_[j & 3], sn = j < 4 ? rs0_[j & 3] : rs1_[j & 3];
;         const float x1 = bf2f((bf16_t)qf[4][j]), x2 = bf2f((bf16_t)qf[5][j]);
;         qf[4][j] = (short)bf1(x1 * cs - x2 * sn); qf[5][j] = (short)bf1(x2 * cs + x1 * sn); }
;     *(LAS v4u*)(lds + lKn) = rk; if (tid < 256) *(LAS v4u*)(lds + lKr) = rr; *(LAS u32x2*)(lds + lVt) = (u32x2){rv.x, rv.y}; *(LAS u32x2*)(lds + lVt + 8) = (u32x2){rv.z, rv.w};
;     __syncthreads();
; #pragma unroll 1
;     for (int step = 0; step < nsteps; ++step) {
;         const int nx = (step + 1 < nsteps) ? step + 1 : step;
;         rk = *(const v4u*)(gKn + (size_t)nx * 64 * 512); rr = *(const v4u*)(gKr + (size_t)nx * 64 * 32); rv = *(const v4u*)(gVt + nx * 64);
;         const LAS unsigned char* Kb = lds + (step & 1) * ML_STAGE;
;         const LAS unsigned char* Vb = Kb + MLK_BYTES;
;         if (64 * step <= q0) {
;             f32x16 acc[2];
;             {
;                 bf16x8 kf[2][6];
; #pragma unroll
;                 for (int sub = 0; sub < 2; ++sub)
; #pragma unroll
;                     for (int kk = 0; kk < 6; ++kk) kf[sub][kk] = *(const LAS bf16x8*)(Kb + (32 * sub + l31) * (MLK_PITCH * 2) + (16 * kk + 8 * hi) * 2);
;                 __builtin_amdgcn_sched_barrier(0);
; #pragma unroll
;                 for (int r = 0; r < 16; ++r) { acc[0][r] = 0.f; acc[1][r] = 0.f; }
; #pragma unroll
;                 for (int kk = 0; kk < 6; ++kk) { acc[0] = MFMA32(kf[0][kk], qf[kk], acc[0]); acc[1] = MFMA32(kf[1][kk], qf[kk], acc[1]); }
.LBB0_1592:
	s_or_b64 exec, exec, s[38:39]
	v_and_b32_e32 v35, 0xffff0000, v16
	v_lshlrev_b32_e32 v34, 16, v16
	v_and_b32_e32 v33, 0xffff0000, v20
	v_lshlrev_b32_e32 v32, 16, v20
	v_pk_mul_f32 v[36:37], v[24:25], v[34:35]
	v_lshlrev_b32_e32 v20, 16, v17
	v_pk_fma_f32 v[36:37], v[28:29], v[32:33], v[36:37]
	v_pk_mul_f32 v[28:29], v[28:29], v[34:35]
	s_waitcnt vmcnt(0)
	ds_write2_b64 v1, v[4:5], v[6:7] offset1:1
	v_pk_fma_f32 v[24:25], v[24:25], v[32:33], v[28:29] neg_lo:[0,0,1] neg_hi:[0,0,1]
	v_mov_b32_e32 v3, v2
	v_cvt_pk_bf16_f32 v88, v24, v25
	v_and_b32_e32 v25, 0xffff0000, v21
	v_lshlrev_b32_e32 v24, 16, v21
	v_and_b32_e32 v21, 0xffff0000, v17
	v_pk_mul_f32 v[16:17], v[26:27], v[20:21]
	v_mov_b32_e32 v4, v2
	v_pk_fma_f32 v[16:17], v[30:31], v[24:25], v[16:17]
	v_mov_b32_e32 v5, v2
	v_cvt_pk_bf16_f32 v85, v16, v17
	v_pk_mul_f32 v[16:17], v[30:31], v[20:21]
	v_and_b32_e32 v21, 0xffff0000, v18
	v_pk_fma_f32 v[16:17], v[26:27], v[24:25], v[16:17] neg_lo:[0,0,1] neg_hi:[0,0,1]
	v_lshlrev_b32_e32 v20, 16, v18
	v_cvt_pk_bf16_f32 v89, v16, v17
	v_and_b32_e32 v17, 0xffff0000, v22
	v_lshlrev_b32_e32 v16, 16, v22
	v_pk_mul_f32 v[24:25], v[12:13], v[16:17]
	v_pk_mul_f32 v[12:13], v[12:13], v[20:21]
	v_pk_fma_f32 v[24:25], v[8:9], v[20:21], v[24:25]
	v_pk_fma_f32 v[8:9], v[8:9], v[16:17], v[12:13] neg_lo:[0,0,1] neg_hi:[0,0,1]
	v_and_b32_e32 v13, 0xffff0000, v19
	v_cvt_pk_bf16_f32 v90, v8, v9
	v_and_b32_e32 v9, 0xffff0000, v23
	v_lshlrev_b32_e32 v8, 16, v23
	v_lshlrev_b32_e32 v12, 16, v19
	v_pk_mul_f32 v[16:17], v[14:15], v[8:9]
	v_cvt_pk_bf16_f32 v86, v24, v25
	v_pk_fma_f32 v[16:17], v[10:11], v[12:13], v[16:17]
	v_pk_mul_f32 v[12:13], v[14:15], v[12:13]
	v_cvt_pk_bf16_f32 v87, v16, v17
	v_pk_fma_f32 v[8:9], v[10:11], v[8:9], v[12:13] neg_lo:[0,0,1] neg_hi:[0,0,1]
	v_mov_b32_e32 v16, v2
	v_mov_b32_e32 v17, v2
	v_cvt_pk_bf16_f32 v91, v8, v9
	v_mov_b32_e32 v6, v2
	v_mov_b32_e32 v7, v2
	v_mov_b32_e32 v8, v2
	v_mov_b32_e32 v9, v2
	v_mov_b32_e32 v10, v2
	v_mov_b32_e32 v11, v2
	v_mov_b32_e32 v12, v2
	v_mov_b32_e32 v13, v2
	v_mov_b32_e32 v14, v2
	v_mov_b32_e32 v15, v2
	v_mov_b64_e32 v[34:35], v[16:17]
	s_lshl_b32 s19, s0, 2
	v_mov_b64_e32 v[32:33], v[14:15]
	v_mov_b64_e32 v[30:31], v[12:13]
	v_mov_b64_e32 v[28:29], v[10:11]
	v_mov_b64_e32 v[26:27], v[8:9]
	v_mov_b64_e32 v[24:25], v[6:7]
	v_mov_b64_e32 v[22:23], v[4:5]
	v_mov_b64_e32 v[20:21], v[2:3]
	v_mov_b64_e32 v[18:19], v[16:17]
	v_or_b32_e32 v159, s18, v136
	v_cvt_pk_bf16_f32 v84, v36, v37
	s_add_i32 s19, s19, 4
	s_addk_i32 s21, 0x100
	s_mov_b32 s40, 0
	v_mov_b32_e32 v163, 0xf149f2ca
	v_mov_b32_e32 v161, 0
	v_mov_b64_e32 v[16:17], v[14:15]
	v_mov_b64_e32 v[14:15], v[12:13]
	v_mov_b64_e32 v[12:13], v[10:11]
	v_mov_b64_e32 v[10:11], v[8:9]
	v_mov_b64_e32 v[8:9], v[6:7]
	v_mov_b64_e32 v[6:7], v[4:5]
	v_mov_b64_e32 v[4:5], v[2:3]
	s_mov_b32 s0, 0
	s_mov_b32 s12, 1
	s_lshl_b64 s[2:3], s[12:13], 16
	v_lshl_add_u64 v[36:37], v[168:169], 0, s[2:3]
	s_lshl_b64 s[2:3], s[12:13], 12
	s_lshl_b32 s12, s12, 6
	v_lshl_add_u64 v[38:39], v[170:171], 0, s[2:3]
	global_load_dwordx4 v[100:103], v[36:37], off
	global_load_dwordx4 v[92:95], v[38:39], off
	v_lshl_add_u64 v[36:37], s[12:13], 1, v[172:173]
	global_load_dwordx4 v[96:99], v[36:37], off
	s_waitcnt lgkmcnt(0)
	s_barrier
	s_cmp_eq_u64 s[8:9], 0
	s_cbranch_scc0 .Lmla_lead_in
	s_barrier
.Lmla_lead_in:
.LBB0_1593:
	s_add_i32 s41, s0, 1
	s_cmp_gt_i32 s40, s18
	s_cbranch_scc1 .Lmla_stage
	s_bitcmp1_b32 s0, 0
	s_cselect_b32 s0, 0x5600, 0
	s_add_i32 s0, s0, 0
	v_add_u32_e32 v3, s0, v138
	v_add_u32_e32 v36, v3, v151
	v_add_u32_e32 v3, v3, v176
	ds_read_b128 v[52:55], v36
	ds_read_b128 v[104:107], v36 offset:32
	ds_read_b128 v[108:111], v36 offset:64
	ds_read_b128 v[112:115], v36 offset:96
	ds_read_b128 v[116:119], v36 offset:128
	ds_read_b128 v[184:187], v36 offset:160
	ds_read_b128 v[36:39], v3
	ds_read_b128 v[56:59], v3 offset:32
	ds_read_b128 v[60:63], v3 offset:64
	ds_read_b128 v[64:67], v3 offset:96
	ds_read_b128 v[120:123], v3 offset:128
	ds_read_b128 v[124:127], v3 offset:160
	s_waitcnt lgkmcnt(5)
	v_mfma_f32_32x32x16_bf16 v[36:51], v[36:39], v[68:71], 0
	v_add_u32_e32 v3, s0, v137
	s_waitcnt lgkmcnt(4)
	v_mfma_f32_32x32x16_bf16 v[36:51], v[56:59], v[72:75], v[36:51]
	s_waitcnt lgkmcnt(3)
	v_mfma_f32_32x32x16_bf16 v[36:51], v[60:63], v[76:79], v[36:51]
	s_waitcnt lgkmcnt(2)
	v_mfma_f32_32x32x16_bf16 v[36:51], v[64:67], v[80:83], v[36:51]
	v_mfma_f32_32x32x16_bf16 v[52:67], v[52:55], v[68:71], 0
	v_mfma_f32_32x32x16_bf16 v[52:67], v[104:107], v[72:75], v[52:67]
	v_add_u32_e32 v104, v3, v177
	v_add_u32_e32 v3, v3, v178
	v_add_u32_e32 v104, 0x3000, v104
	v_add_u32_e32 v3, 0x3000, v3
	v_mfma_f32_32x32x16_bf16 v[52:67], v[108:111], v[76:79], v[52:67]
	v_mfma_f32_32x32x16_bf16 v[52:67], v[112:115], v[80:83], v[52:67]
	s_waitcnt lgkmcnt(1)
	v_mfma_f32_32x32x16_bf16 v[36:51], v[120:123], v[88:91], v[36:51]
	v_mfma_f32_32x32x16_bf16 v[52:67], v[116:119], v[88:91], v[52:67]
	s_waitcnt lgkmcnt(0)
	v_mfma_f32_32x32x16_bf16 v[36:51], v[124:127], v[84:87], v[36:51]
	ds_read2_b64 v[132:135], v104 offset0:128 offset1:130
	ds_read2_b64 v[124:127], v104 offset0:132 offset1:134
	ds_read2_b64 v[128:131], v3 offset0:128 offset1:130
	ds_read2_b64 v[120:123], v3 offset0:132 offset1:134
	ds_read2_b64 v[116:119], v104 offset0:136 offset1:138
	ds_read2_b64 v[108:111], v104 offset0:140 offset1:142
	ds_read2_b64 v[112:115], v3 offset0:136 offset1:138
	ds_read2_b64 v[104:107], v3 offset0:140 offset1:142
	v_mfma_f32_32x32x16_bf16 v[52:67], v[184:187], v[84:87], v[52:67]

; #define LAS __attribute__((address_space(3)))
; __device__ __forceinline__ int crow(int r, int hi) { return (r & 3) + 8 * (r >> 2) + 4 * hi; }
; __device__ __forceinline__ void mla_block(int bh, int sb, int tid, int lane, int wave, LAS unsigned char* lds, const bf16_t* __restrict__ QM, const bf16_t* __restrict__ KVM, const bf16_t* __restrict__ KPE, ...
;     ...
;             float tmax = -1e30f;
; #pragma unroll
;             for (int sub = 0; sub < 2; ++sub) { const int s0 = 64 * step + 32 * sub;
;                 if (s0 + 31 > q0) {
; #pragma unroll
;                     for (int r = 0; r < 16; ++r) if ((s0 + crow(r, hi)) > t) acc[sub][r] = -1e30f; }
; #pragma unroll
;                 for (int r = 0; r < 16; ++r) tmax = fmaxf(tmax, acc[sub][r]); }
;     ...
;         LAS unsigned char* nb = lds + ((step + 1) & 1) * ML_STAGE;
;         *(LAS v4u*)(nb + lKn) = rk; if (tid < 256) *(LAS v4u*)(nb + lKr) = rr; *(LAS u32x2*)(nb + lVt) = (u32x2){rv.x, rv.y}; *(LAS u32x2*)(nb + lVt + 8) = (u32x2){rv.z, rv.w};
;         __syncthreads();
.LBB0_1603:
	s_or_b64 exec, exec, s[38:39]
	v_add_u32_e32 v3, s0, v152
	v_add_u32_e32 v3, 0x3400, v3
	s_waitcnt vmcnt(0)
	ds_write2_b64 v3, v[96:97], v[98:99] offset1:1
	s_add_i32 s12, s41, 1
	s_add_i32 s0, s19, -1
	s_min_u32 s12, s12, s0
	s_lshl_b64 s[2:3], s[12:13], 16
	v_lshl_add_u64 v[184:185], v[168:169], 0, s[2:3]
	s_lshl_b64 s[2:3], s[12:13], 12
	s_lshl_b32 s12, s12, 6
	v_lshl_add_u64 v[186:187], v[170:171], 0, s[2:3]
	global_load_dwordx4 v[100:103], v[184:185], off
	global_load_dwordx4 v[92:95], v[186:187], off
	v_lshl_add_u64 v[184:185], s[12:13], 1, v[172:173]
	global_load_dwordx4 v[96:99], v[184:185], off
	s_waitcnt lgkmcnt(0)
	s_barrier
	s_cmp_gt_i32 s40, s18
	s_cbranch_scc1 .LBB0_1601
	s_add_i32 s0, s40, 31
	s_cmp_le_i32 s0, s18
	v_add_u32_e32 v3, s40, v147
	s_cbranch_scc1 .LBB0_1596
	v_cmp_gt_i32_e32 vcc, v3, v159
	s_nop 6
	v_cndmask_b32_e32 v165, v52, v183, vcc
	v_cmp_lt_i32_e32 vcc, v3, v159
	s_nop 1
	v_cndmask_b32_e32 v52, v165, v52, vcc
	v_add_u32_e32 v165, 2, v3
	v_cndmask_b32_e32 v53, v183, v53, vcc
	v_cmp_le_i32_e32 vcc, v165, v159
	v_add_u32_e32 v165, 3, v3
	s_nop 0
	v_cndmask_b32_e32 v54, v183, v54, vcc
	v_cmp_le_i32_e32 vcc, v165, v159
	v_add_u32_e32 v165, 8, v3
	s_nop 0
	v_cndmask_b32_e32 v55, v183, v55, vcc
	v_cmp_le_i32_e32 vcc, v165, v159
	v_add_u32_e32 v165, 9, v3
	s_nop 0
	v_cndmask_b32_e32 v56, v183, v56, vcc
	v_cmp_le_i32_e32 vcc, v165, v159
	v_add_u32_e32 v165, 10, v3
	s_nop 0
	v_cndmask_b32_e32 v57, v183, v57, vcc
	v_cmp_le_i32_e32 vcc, v165, v159
	v_add_u32_e32 v165, 11, v3
	s_nop 0
	v_cndmask_b32_e32 v58, v183, v58, vcc
	v_cmp_le_i32_e32 vcc, v165, v159
	v_add_u32_e32 v165, 16, v3
	s_nop 0
	v_cndmask_b32_e32 v59, v183, v59, vcc
	v_cmp_le_i32_e32 vcc, v165, v159
	v_add_u32_e32 v165, 17, v3
	s_nop 0
	v_cndmask_b32_e32 v60, v183, v60, vcc
	v_cmp_le_i32_e32 vcc, v165, v159
	v_add_u32_e32 v165, 18, v3
	s_nop 0
	v_cndmask_b32_e32 v61, v183, v61, vcc
	v_cmp_le_i32_e32 vcc, v165, v159
	v_add_u32_e32 v165, 19, v3
	s_nop 0
	v_cndmask_b32_e32 v62, v183, v62, vcc
	v_cmp_le_i32_e32 vcc, v165, v159
	v_add_u32_e32 v165, 24, v3
	s_nop 0
	v_cndmask_b32_e32 v63, v183, v63, vcc
	v_cmp_le_i32_e32 vcc, v165, v159
	v_add_u32_e32 v165, 25, v3
	s_nop 0
	v_cndmask_b32_e32 v64, v183, v64, vcc
	v_cmp_le_i32_e32 vcc, v165, v159
	v_add_u32_e32 v165, 26, v3
	s_nop 0
	v_cndmask_b32_e32 v65, v183, v65, vcc
	v_cmp_le_i32_e32 vcc, v165, v159
	v_add_u32_e32 v165, 27, v3
	s_nop 0
	v_cndmask_b32_e32 v66, v183, v66, vcc
	v_cmp_le_i32_e32 vcc, v165, v159
	s_nop 1
	v_cndmask_b32_e32 v67, v183, v67, vcc

; #define LAS __attribute__((address_space(3)))
; __device__ __forceinline__ void mla_block(int bh, int sb, int tid, int lane, int wave, LAS unsigned char* lds, const bf16_t* __restrict__ QM, const bf16_t* __restrict__ KVM, const bf16_t* __restrict__ KPE, ...
;     ...
;         LAS unsigned char* nb = lds + ((step + 1) & 1) * ML_STAGE;
;         *(LAS v4u*)(nb + lKn) = rk; if (tid < 256) *(LAS v4u*)(nb + lKr) = rr; *(LAS u32x2*)(nb + lVt) = (u32x2){rv.x, rv.y}; *(LAS u32x2*)(nb + lVt + 8) = (u32x2){rv.z, rv.w};
;         __syncthreads();
;     }
.LBB0_1601:
	s_add_i32 s40, s40, 64
	s_cmp_lg_u32 s21, s40
	s_barrier
	s_cbranch_scc0 .Lmla_exit
	s_mov_b32 s0, s41
	s_branch .LBB0_1593
.Lmla_exit:
	s_cmp_eq_u64 s[8:9], 0
	s_cbranch_scc1 .LBB0_1576
	s_barrier
	s_branch .LBB0_1576
